# GEMM mainloop heads aligned to 64 bytes (code placement)
# baseline (speedup 1.0000x reference)
; template <class Epi, class Sched, bool ALIGN_EPI = false, bool SP2 = false>
; __device__ __forceinline__ void gemm_phase(PG8_LAS unsigned char* lds, const Gemm g, const Sched& S, const Epi& E) {
;     ...
;         const bool has_next = S.next(ui + 1, nxt);
;         const char* nA = has_next ? (const char*)g.A + (size_t)nxt.pm * tstep : cA; const char* nB = has_next ? (const char*)g.Bt + (size_t)nxt.pn * tstep : cB;
;         for (int t = 0; t < nt; t += 2) {
;             const bool last = (t == nt - 2);
;             const char* a1 = cA + (size_t)(t + 1) * kstep;
;             const char* a2 = last ? nA : cA + (size_t)(t + 2) * kstep; const char* b2 = last ? nB : cB + (size_t)(t + 2) * kstep;
;     ...
; #pragma unroll
;         for (int a = 0; a < 2; ++a)
; #pragma unroll
;             for (int b = 0; b < 2; ++b)
; #pragma unroll
;                 for (int m = 0; m < 4; ++m)
; #pragma unroll
;                     for (int n = 0; n < 2; ++n) acc[a][b][m][n] = (f32x4){0.f, 0.f, 0.f, 0.f};
;         cur = nxt; cA = nA; cB = nB; ++ui;
.LBB0_216:
	s_ashr_i32 s41, s40, 31
	s_lshl_b64 s[42:43], s[40:41], 20
	s_add_u32 s42, s62, s42
	s_addc_u32 s43, s63, s43
	s_and_b64 s[44:45], s[6:7], exec
	s_cselect_b32 s9, s43, s11
	s_cselect_b32 s15, s42, s10
	s_ashr_i32 s39, s38, 31
	s_lshl_b64 s[44:45], s[38:39], 20
	s_add_u32 s44, s64, s44
	s_addc_u32 s45, s65, s45
	s_and_b64 s[46:47], s[6:7], exec
	s_cselect_b32 s33, s45, s13
	s_cselect_b32 s39, s44, s12
	s_add_u32 s10, s10, 0x80080
	s_addc_u32 s11, s11, 0
	s_add_u32 s41, s12, 0x100
	v_mov_b32_e32 v0, 0
	s_addc_u32 s48, s13, 0
	s_mov_b32 s49, -2
	s_waitcnt lgkmcnt(0)
	v_mov_b32_e32 v1, v0
	v_mov_b32_e32 v2, v0
	v_mov_b32_e32 v3, v0
	v_mov_b32_e32 v4, v0
	v_mov_b32_e32 v5, v0
	v_mov_b32_e32 v6, v0
	v_mov_b32_e32 v7, v0
	v_mov_b32_e32 v16, v0
	v_mov_b32_e32 v17, v0
	v_mov_b32_e32 v18, v0
	v_mov_b32_e32 v19, v0
	v_mov_b32_e32 v20, v0
	v_mov_b32_e32 v21, v0
	v_mov_b32_e32 v22, v0
	v_mov_b32_e32 v23, v0
	v_mov_b32_e32 v32, v0
	v_mov_b32_e32 v33, v0
	v_mov_b32_e32 v34, v0
	v_mov_b32_e32 v35, v0
	v_mov_b32_e32 v36, v0
	v_mov_b32_e32 v37, v0
	v_mov_b32_e32 v38, v0
	v_mov_b32_e32 v39, v0
	v_mov_b32_e32 v48, v0
	v_mov_b32_e32 v49, v0
	v_mov_b32_e32 v50, v0
	v_mov_b32_e32 v51, v0
	v_mov_b32_e32 v52, v0
	v_mov_b32_e32 v53, v0
	v_mov_b32_e32 v54, v0
	v_mov_b32_e32 v55, v0
	v_mov_b32_e32 v8, v0
	v_mov_b32_e32 v9, v0
	v_mov_b32_e32 v10, v0
	v_mov_b32_e32 v11, v0
	v_mov_b32_e32 v12, v0
	v_mov_b32_e32 v13, v0
	v_mov_b32_e32 v14, v0
	v_mov_b32_e32 v15, v0
	v_mov_b32_e32 v24, v0
	v_mov_b32_e32 v25, v0
	v_mov_b32_e32 v26, v0
	v_mov_b32_e32 v27, v0
	v_mov_b32_e32 v28, v0
	v_mov_b32_e32 v29, v0
	v_mov_b32_e32 v30, v0
	v_mov_b32_e32 v31, v0
	v_mov_b32_e32 v40, v0
	v_mov_b32_e32 v41, v0
	v_mov_b32_e32 v42, v0
	v_mov_b32_e32 v43, v0
	v_mov_b32_e32 v44, v0
	v_mov_b32_e32 v45, v0
	v_mov_b32_e32 v46, v0
	v_mov_b32_e32 v47, v0
	v_mov_b32_e32 v56, v0
	v_mov_b32_e32 v57, v0
	v_mov_b32_e32 v58, v0
	v_mov_b32_e32 v59, v0
	v_mov_b32_e32 v60, v0
	v_mov_b32_e32 v61, v0
	v_mov_b32_e32 v62, v0
	v_mov_b32_e32 v63, v0
	v_mov_b32_e32 v64, v0
	v_mov_b32_e32 v65, v0
	v_mov_b32_e32 v66, v0
	v_mov_b32_e32 v67, v0
	v_mov_b32_e32 v68, v0
	v_mov_b32_e32 v69, v0
	v_mov_b32_e32 v70, v0
	v_mov_b32_e32 v71, v0
	v_mov_b32_e32 v80, v0
	v_mov_b32_e32 v81, v0
	v_mov_b32_e32 v82, v0
	v_mov_b32_e32 v83, v0
	v_mov_b32_e32 v84, v0
	v_mov_b32_e32 v85, v0
	v_mov_b32_e32 v86, v0
	v_mov_b32_e32 v87, v0
	v_mov_b32_e32 v96, v0
	v_mov_b32_e32 v97, v0
	v_mov_b32_e32 v98, v0
	v_mov_b32_e32 v99, v0
	v_mov_b32_e32 v100, v0
	v_mov_b32_e32 v101, v0
	v_mov_b32_e32 v102, v0
	v_mov_b32_e32 v103, v0
	v_mov_b32_e32 v112, v0
	v_mov_b32_e32 v113, v0
	v_mov_b32_e32 v114, v0
	v_mov_b32_e32 v115, v0
	v_mov_b32_e32 v116, v0
	v_mov_b32_e32 v117, v0
	v_mov_b32_e32 v118, v0
	v_mov_b32_e32 v119, v0
	v_mov_b32_e32 v72, v0
	v_mov_b32_e32 v73, v0
	v_mov_b32_e32 v74, v0
	v_mov_b32_e32 v75, v0
	v_mov_b32_e32 v76, v0
	v_mov_b32_e32 v77, v0
	v_mov_b32_e32 v78, v0
	v_mov_b32_e32 v79, v0
	v_mov_b32_e32 v88, v0
	v_mov_b32_e32 v89, v0
	v_mov_b32_e32 v90, v0
	v_mov_b32_e32 v91, v0
	v_mov_b32_e32 v92, v0
	v_mov_b32_e32 v93, v0
	v_mov_b32_e32 v94, v0
	v_mov_b32_e32 v95, v0
	v_mov_b32_e32 v104, v0
	v_mov_b32_e32 v105, v0
	v_mov_b32_e32 v106, v0
	v_mov_b32_e32 v107, v0
	v_mov_b32_e32 v108, v0
	v_mov_b32_e32 v109, v0
	v_mov_b32_e32 v110, v0
	v_mov_b32_e32 v111, v0
	v_mov_b32_e32 v120, v0
	v_mov_b32_e32 v121, v0
	v_mov_b32_e32 v122, v0
	v_mov_b32_e32 v123, v0
	v_mov_b32_e32 v124, v0
	v_mov_b32_e32 v125, v0
	v_mov_b32_e32 v126, v0
	v_mov_b32_e32 v127, v0
	.p2align 6

; template <class Epi, class Sched, bool ALIGN_EPI = false, bool SP2 = false>
; __device__ __forceinline__ void gemm_phase(PG8_LAS unsigned char* lds, const Gemm g, const Sched& S, const Epi& E) {
;     ...
;         const bool has_next = S.next(ui + 1, nxt);
;         const char* nA = has_next ? (const char*)g.A + (size_t)nxt.pm * tstep : cA; const char* nB = has_next ? (const char*)g.Bt + (size_t)nxt.pn * tstep : cB;
;         for (int t = 0; t < nt; t += 2) {
;             const bool last = (t == nt - 2);
;             const char* a1 = cA + (size_t)(t + 1) * kstep;
;             const char* a2 = last ? nA : cA + (size_t)(t + 2) * kstep; const char* b2 = last ? nB : cB + (size_t)(t + 2) * kstep;
;     ...
; #pragma unroll
;         for (int a = 0; a < 2; ++a)
; #pragma unroll
;             for (int b = 0; b < 2; ++b)
; #pragma unroll
;                 for (int m = 0; m < 4; ++m)
; #pragma unroll
;                     for (int n = 0; n < 2; ++n) acc[a][b][m][n] = (f32x4){0.f, 0.f, 0.f, 0.f};
;         cur = nxt; cA = nA; cB = nB; ++ui;
.LBB0_566:
	s_ashr_i32 s25, s24, 31
	s_lshl_b64 s[26:27], s[24:25], 18
	s_add_u32 s26, s40, s26
	s_addc_u32 s27, s41, s27
	s_and_b64 s[28:29], s[4:5], exec
	s_cselect_b32 s7, s27, s35
	s_cselect_b32 s25, s26, s34
	s_ashr_i32 s23, s22, 31
	s_lshl_b64 s[28:29], s[22:23], 18
	s_add_u32 s28, s42, s28
	s_addc_u32 s29, s43, s29
	s_and_b64 s[38:39], s[4:5], exec
	s_cselect_b32 s23, s29, s37
	s_cselect_b32 s31, s28, s36
	s_add_u32 s34, s34, 0x20080
	s_addc_u32 s35, s35, 0
	s_add_u32 s33, s36, 0x100
	v_mov_b32_e32 v0, 0
	s_addc_u32 s65, s37, 0
	s_mov_b32 s66, -2
	v_mov_b32_e32 v1, v0
	v_mov_b32_e32 v2, v0
	v_mov_b32_e32 v3, v0
	v_mov_b32_e32 v4, v0
	v_mov_b32_e32 v5, v0
	v_mov_b32_e32 v6, v0
	v_mov_b32_e32 v7, v0
	v_mov_b32_e32 v16, v0
	v_mov_b32_e32 v17, v0
	v_mov_b32_e32 v18, v0
	v_mov_b32_e32 v19, v0
	v_mov_b32_e32 v20, v0
	v_mov_b32_e32 v21, v0
	v_mov_b32_e32 v22, v0
	v_mov_b32_e32 v23, v0
	v_mov_b32_e32 v32, v0
	v_mov_b32_e32 v33, v0
	v_mov_b32_e32 v34, v0
	v_mov_b32_e32 v35, v0
	v_mov_b32_e32 v36, v0
	v_mov_b32_e32 v37, v0
	v_mov_b32_e32 v38, v0
	v_mov_b32_e32 v39, v0
	v_mov_b32_e32 v48, v0
	v_mov_b32_e32 v49, v0
	v_mov_b32_e32 v50, v0
	v_mov_b32_e32 v51, v0
	v_mov_b32_e32 v52, v0
	v_mov_b32_e32 v53, v0
	v_mov_b32_e32 v54, v0
	v_mov_b32_e32 v55, v0
	v_mov_b32_e32 v8, v0
	v_mov_b32_e32 v9, v0
	v_mov_b32_e32 v10, v0
	v_mov_b32_e32 v11, v0
	v_mov_b32_e32 v12, v0
	v_mov_b32_e32 v13, v0
	v_mov_b32_e32 v14, v0
	v_mov_b32_e32 v15, v0
	v_mov_b32_e32 v24, v0
	v_mov_b32_e32 v25, v0
	v_mov_b32_e32 v26, v0
	v_mov_b32_e32 v27, v0
	v_mov_b32_e32 v28, v0
	v_mov_b32_e32 v29, v0
	v_mov_b32_e32 v30, v0
	v_mov_b32_e32 v31, v0
	v_mov_b32_e32 v40, v0
	v_mov_b32_e32 v41, v0
	v_mov_b32_e32 v42, v0
	v_mov_b32_e32 v43, v0
	v_mov_b32_e32 v44, v0
	v_mov_b32_e32 v45, v0
	v_mov_b32_e32 v46, v0
	v_mov_b32_e32 v47, v0
	v_mov_b32_e32 v56, v0
	v_mov_b32_e32 v57, v0
	v_mov_b32_e32 v58, v0
	v_mov_b32_e32 v59, v0
	v_mov_b32_e32 v60, v0
	v_mov_b32_e32 v61, v0
	v_mov_b32_e32 v62, v0
	v_mov_b32_e32 v63, v0
	v_mov_b32_e32 v64, v0
	v_mov_b32_e32 v65, v0
	v_mov_b32_e32 v66, v0
	v_mov_b32_e32 v67, v0
	v_mov_b32_e32 v68, v0
	v_mov_b32_e32 v69, v0
	v_mov_b32_e32 v70, v0
	v_mov_b32_e32 v71, v0
	v_mov_b32_e32 v80, v0
	v_mov_b32_e32 v81, v0
	v_mov_b32_e32 v82, v0
	v_mov_b32_e32 v83, v0
	v_mov_b32_e32 v84, v0
	v_mov_b32_e32 v85, v0
	v_mov_b32_e32 v86, v0
	v_mov_b32_e32 v87, v0
	v_mov_b32_e32 v96, v0
	v_mov_b32_e32 v97, v0
	v_mov_b32_e32 v98, v0
	v_mov_b32_e32 v99, v0
	v_mov_b32_e32 v100, v0
	v_mov_b32_e32 v101, v0
	v_mov_b32_e32 v102, v0
	v_mov_b32_e32 v103, v0
	v_mov_b32_e32 v112, v0
	v_mov_b32_e32 v113, v0
	v_mov_b32_e32 v114, v0
	v_mov_b32_e32 v115, v0
	v_mov_b32_e32 v116, v0
	v_mov_b32_e32 v117, v0
	v_mov_b32_e32 v118, v0
	v_mov_b32_e32 v119, v0
	v_mov_b32_e32 v72, v0
	v_mov_b32_e32 v73, v0
	v_mov_b32_e32 v74, v0
	v_mov_b32_e32 v75, v0
	v_mov_b32_e32 v76, v0
	v_mov_b32_e32 v77, v0
	v_mov_b32_e32 v78, v0
	v_mov_b32_e32 v79, v0
	v_mov_b32_e32 v88, v0
	v_mov_b32_e32 v89, v0
	v_mov_b32_e32 v90, v0
	v_mov_b32_e32 v91, v0
	v_mov_b32_e32 v92, v0
	v_mov_b32_e32 v93, v0
	v_mov_b32_e32 v94, v0
	v_mov_b32_e32 v95, v0
	v_mov_b32_e32 v104, v0
	v_mov_b32_e32 v105, v0
	v_mov_b32_e32 v106, v0
	v_mov_b32_e32 v107, v0
	v_mov_b32_e32 v108, v0
	v_mov_b32_e32 v109, v0
	v_mov_b32_e32 v110, v0
	v_mov_b32_e32 v111, v0
	v_mov_b32_e32 v120, v0
	v_mov_b32_e32 v121, v0
	v_mov_b32_e32 v122, v0
	v_mov_b32_e32 v123, v0
	v_mov_b32_e32 v124, v0
	v_mov_b32_e32 v125, v0
	v_mov_b32_e32 v126, v0
	v_mov_b32_e32 v127, v0
	.p2align 6

; template <class Epi, class Sched, bool ALIGN_EPI = false, bool SP2 = false>
; __device__ __forceinline__ void gemm_phase(PG8_LAS unsigned char* lds, const Gemm g, const Sched& S, const Epi& E) {
;     ...
;         const bool has_next = S.next(ui + 1, nxt);
;         const char* nA = has_next ? (const char*)g.A + (size_t)nxt.pm * tstep : cA; const char* nB = has_next ? (const char*)g.Bt + (size_t)nxt.pn * tstep : cB;
;         for (int t = 0; t < nt; t += 2) {
;             const bool last = (t == nt - 2);
;             const char* a1 = cA + (size_t)(t + 1) * kstep;
;             const char* a2 = last ? nA : cA + (size_t)(t + 2) * kstep; const char* b2 = last ? nB : cB + (size_t)(t + 2) * kstep;
;     ...
; #pragma unroll
;         for (int a = 0; a < 2; ++a)
; #pragma unroll
;             for (int b = 0; b < 2; ++b)
; #pragma unroll
;                 for (int m = 0; m < 4; ++m)
; #pragma unroll
;                     for (int n = 0; n < 2; ++n) acc[a][b][m][n] = (f32x4){0.f, 0.f, 0.f, 0.f};
;         cur = nxt; cA = nA; cB = nB; ++ui;
.LBB0_622:
	s_ashr_i32 s17, s16, 31
	s_lshl_b64 s[18:19], s[16:17], 18
	s_add_u32 s18, s31, s18
	s_addc_u32 s19, s33, s19
	s_and_b64 s[20:21], s[4:5], exec
	s_cselect_b32 s17, s19, s25
	s_cselect_b32 s51, s18, s24
	s_ashr_i32 s15, s14, 31
	s_lshl_b64 s[20:21], s[14:15], 18
	s_add_u32 s20, s34, s20
	s_addc_u32 s21, s35, s21
	s_and_b64 s[28:29], s[4:5], exec
	s_cselect_b32 s15, s21, s27
	s_cselect_b32 s52, s20, s26
	s_add_u32 s24, s24, 0x20080
	s_addc_u32 s25, s25, 0
	s_add_u32 s53, s26, 0x100
	v_mov_b32_e32 v0, 0
	s_addc_u32 s54, s27, 0
	s_mov_b32 s55, -2
	v_mov_b32_e32 v1, v0
	v_mov_b32_e32 v2, v0
	v_mov_b32_e32 v3, v0
	v_mov_b32_e32 v4, v0
	v_mov_b32_e32 v5, v0
	v_mov_b32_e32 v6, v0
	v_mov_b32_e32 v7, v0
	v_mov_b32_e32 v16, v0
	v_mov_b32_e32 v17, v0
	v_mov_b32_e32 v18, v0
	v_mov_b32_e32 v19, v0
	v_mov_b32_e32 v20, v0
	v_mov_b32_e32 v21, v0
	v_mov_b32_e32 v22, v0
	v_mov_b32_e32 v23, v0
	v_mov_b32_e32 v32, v0
	v_mov_b32_e32 v33, v0
	v_mov_b32_e32 v34, v0
	v_mov_b32_e32 v35, v0
	v_mov_b32_e32 v36, v0
	v_mov_b32_e32 v37, v0
	v_mov_b32_e32 v38, v0
	v_mov_b32_e32 v39, v0
	v_mov_b32_e32 v48, v0
	v_mov_b32_e32 v49, v0
	v_mov_b32_e32 v50, v0
	v_mov_b32_e32 v51, v0
	v_mov_b32_e32 v52, v0
	v_mov_b32_e32 v53, v0
	v_mov_b32_e32 v54, v0
	v_mov_b32_e32 v55, v0
	v_mov_b32_e32 v8, v0
	v_mov_b32_e32 v9, v0
	v_mov_b32_e32 v10, v0
	v_mov_b32_e32 v11, v0
	v_mov_b32_e32 v12, v0
	v_mov_b32_e32 v13, v0
	v_mov_b32_e32 v14, v0
	v_mov_b32_e32 v15, v0
	v_mov_b32_e32 v24, v0
	v_mov_b32_e32 v25, v0
	v_mov_b32_e32 v26, v0
	v_mov_b32_e32 v27, v0
	v_mov_b32_e32 v28, v0
	v_mov_b32_e32 v29, v0
	v_mov_b32_e32 v30, v0
	v_mov_b32_e32 v31, v0
	v_mov_b32_e32 v40, v0
	v_mov_b32_e32 v41, v0
	v_mov_b32_e32 v42, v0
	v_mov_b32_e32 v43, v0
	v_mov_b32_e32 v44, v0
	v_mov_b32_e32 v45, v0
	v_mov_b32_e32 v46, v0
	v_mov_b32_e32 v47, v0
	v_mov_b32_e32 v56, v0
	v_mov_b32_e32 v57, v0
	v_mov_b32_e32 v58, v0
	v_mov_b32_e32 v59, v0
	v_mov_b32_e32 v60, v0
	v_mov_b32_e32 v61, v0
	v_mov_b32_e32 v62, v0
	v_mov_b32_e32 v63, v0
	v_mov_b32_e32 v64, v0
	v_mov_b32_e32 v65, v0
	v_mov_b32_e32 v66, v0
	v_mov_b32_e32 v67, v0
	v_mov_b32_e32 v68, v0
	v_mov_b32_e32 v69, v0
	v_mov_b32_e32 v70, v0
	v_mov_b32_e32 v71, v0
	v_mov_b32_e32 v80, v0
	v_mov_b32_e32 v81, v0
	v_mov_b32_e32 v82, v0
	v_mov_b32_e32 v83, v0
	v_mov_b32_e32 v84, v0
	v_mov_b32_e32 v85, v0
	v_mov_b32_e32 v86, v0
	v_mov_b32_e32 v87, v0
	v_mov_b32_e32 v96, v0
	v_mov_b32_e32 v97, v0
	v_mov_b32_e32 v98, v0
	v_mov_b32_e32 v99, v0
	v_mov_b32_e32 v100, v0
	v_mov_b32_e32 v101, v0
	v_mov_b32_e32 v102, v0
	v_mov_b32_e32 v103, v0
	v_mov_b32_e32 v112, v0
	v_mov_b32_e32 v113, v0
	v_mov_b32_e32 v114, v0
	v_mov_b32_e32 v115, v0
	v_mov_b32_e32 v116, v0
	v_mov_b32_e32 v117, v0
	v_mov_b32_e32 v118, v0
	v_mov_b32_e32 v119, v0
	v_mov_b32_e32 v72, v0
	v_mov_b32_e32 v73, v0
	v_mov_b32_e32 v74, v0
	v_mov_b32_e32 v75, v0
	v_mov_b32_e32 v76, v0
	v_mov_b32_e32 v77, v0
	v_mov_b32_e32 v78, v0
	v_mov_b32_e32 v79, v0
	v_mov_b32_e32 v88, v0
	v_mov_b32_e32 v89, v0
	v_mov_b32_e32 v90, v0
	v_mov_b32_e32 v91, v0
	v_mov_b32_e32 v92, v0
	v_mov_b32_e32 v93, v0
	v_mov_b32_e32 v94, v0
	v_mov_b32_e32 v95, v0
	v_mov_b32_e32 v104, v0
	v_mov_b32_e32 v105, v0
	v_mov_b32_e32 v106, v0
	v_mov_b32_e32 v107, v0
	v_mov_b32_e32 v108, v0
	v_mov_b32_e32 v109, v0
	v_mov_b32_e32 v110, v0
	v_mov_b32_e32 v111, v0
	v_mov_b32_e32 v120, v0
	v_mov_b32_e32 v121, v0
	v_mov_b32_e32 v122, v0
	v_mov_b32_e32 v123, v0
	v_mov_b32_e32 v124, v0
	v_mov_b32_e32 v125, v0
	v_mov_b32_e32 v126, v0
	v_mov_b32_e32 v127, v0
	.p2align 6

; template <class Epi, class Sched, bool ALIGN_EPI = false, bool SP2 = false>
; __device__ __forceinline__ void gemm_phase(PG8_LAS unsigned char* lds, const Gemm g, const Sched& S, const Epi& E) {
;     ...
;         const bool has_next = S.next(ui + 1, nxt);
;         const char* nA = has_next ? (const char*)g.A + (size_t)nxt.pm * tstep : cA; const char* nB = has_next ? (const char*)g.Bt + (size_t)nxt.pn * tstep : cB;
;         for (int t = 0; t < nt; t += 2) {
;             const bool last = (t == nt - 2);
;             const char* a1 = cA + (size_t)(t + 1) * kstep;
;             const char* a2 = last ? nA : cA + (size_t)(t + 2) * kstep; const char* b2 = last ? nB : cB + (size_t)(t + 2) * kstep;
;     ...
; #pragma unroll
;         for (int a = 0; a < 2; ++a)
; #pragma unroll
;             for (int b = 0; b < 2; ++b)
; #pragma unroll
;                 for (int m = 0; m < 4; ++m)
; #pragma unroll
;                     for (int n = 0; n < 2; ++n) acc[a][b][m][n] = (f32x4){0.f, 0.f, 0.f, 0.f};
;         cur = nxt; cA = nA; cB = nB; ++ui;
.LBB0_1048:
	s_ashr_i32 s21, s20, 31
	s_lshl_b64 s[22:23], s[20:21], 19
	s_add_u32 s22, s36, s22
	s_addc_u32 s23, s37, s23
	s_and_b64 s[24:25], s[6:7], exec
	s_cselect_b32 s21, s23, s29
	s_cselect_b32 s50, s22, s28
	s_ashr_i32 s19, s18, 31
	s_lshl_b64 s[24:25], s[18:19], 19
	s_add_u32 s24, s38, s24
	s_addc_u32 s25, s39, s25
	s_and_b64 s[34:35], s[6:7], exec
	s_cselect_b32 s19, s25, s31
	s_cselect_b32 s51, s24, s30
	s_add_u32 s28, s28, 0x40080
	s_addc_u32 s29, s29, 0
	s_add_u32 s52, s30, 0x100
	v_mov_b32_e32 v0, 0
	s_addc_u32 s53, s31, 0
	s_mov_b32 s54, -2
	v_mov_b32_e32 v1, v0
	v_mov_b32_e32 v2, v0
	v_mov_b32_e32 v3, v0
	v_mov_b32_e32 v4, v0
	v_mov_b32_e32 v5, v0
	v_mov_b32_e32 v6, v0
	v_mov_b32_e32 v7, v0
	v_mov_b32_e32 v16, v0
	v_mov_b32_e32 v17, v0
	v_mov_b32_e32 v18, v0
	v_mov_b32_e32 v19, v0
	v_mov_b32_e32 v20, v0
	v_mov_b32_e32 v21, v0
	v_mov_b32_e32 v22, v0
	v_mov_b32_e32 v23, v0
	v_mov_b32_e32 v32, v0
	v_mov_b32_e32 v33, v0
	v_mov_b32_e32 v34, v0
	v_mov_b32_e32 v35, v0
	v_mov_b32_e32 v36, v0
	v_mov_b32_e32 v37, v0
	v_mov_b32_e32 v38, v0
	v_mov_b32_e32 v39, v0
	v_mov_b32_e32 v48, v0
	v_mov_b32_e32 v49, v0
	v_mov_b32_e32 v50, v0
	v_mov_b32_e32 v51, v0
	v_mov_b32_e32 v52, v0
	v_mov_b32_e32 v53, v0
	v_mov_b32_e32 v54, v0
	v_mov_b32_e32 v55, v0
	v_mov_b32_e32 v8, v0
	v_mov_b32_e32 v9, v0
	v_mov_b32_e32 v10, v0
	v_mov_b32_e32 v11, v0
	v_mov_b32_e32 v12, v0
	v_mov_b32_e32 v13, v0
	v_mov_b32_e32 v14, v0
	v_mov_b32_e32 v15, v0
	v_mov_b32_e32 v24, v0
	v_mov_b32_e32 v25, v0
	v_mov_b32_e32 v26, v0
	v_mov_b32_e32 v27, v0
	v_mov_b32_e32 v28, v0
	v_mov_b32_e32 v29, v0
	v_mov_b32_e32 v30, v0
	v_mov_b32_e32 v31, v0
	v_mov_b32_e32 v40, v0
	v_mov_b32_e32 v41, v0
	v_mov_b32_e32 v42, v0
	v_mov_b32_e32 v43, v0
	v_mov_b32_e32 v44, v0
	v_mov_b32_e32 v45, v0
	v_mov_b32_e32 v46, v0
	v_mov_b32_e32 v47, v0
	v_mov_b32_e32 v56, v0
	v_mov_b32_e32 v57, v0
	v_mov_b32_e32 v58, v0
	v_mov_b32_e32 v59, v0
	v_mov_b32_e32 v60, v0
	v_mov_b32_e32 v61, v0
	v_mov_b32_e32 v62, v0
	v_mov_b32_e32 v63, v0
	v_mov_b32_e32 v64, v0
	v_mov_b32_e32 v65, v0
	v_mov_b32_e32 v66, v0
	v_mov_b32_e32 v67, v0
	v_mov_b32_e32 v68, v0
	v_mov_b32_e32 v69, v0
	v_mov_b32_e32 v70, v0
	v_mov_b32_e32 v71, v0
	v_mov_b32_e32 v80, v0
	v_mov_b32_e32 v81, v0
	v_mov_b32_e32 v82, v0
	v_mov_b32_e32 v83, v0
	v_mov_b32_e32 v84, v0
	v_mov_b32_e32 v85, v0
	v_mov_b32_e32 v86, v0
	v_mov_b32_e32 v87, v0
	v_mov_b32_e32 v96, v0
	v_mov_b32_e32 v97, v0
	v_mov_b32_e32 v98, v0
	v_mov_b32_e32 v99, v0
	v_mov_b32_e32 v100, v0
	v_mov_b32_e32 v101, v0
	v_mov_b32_e32 v102, v0
	v_mov_b32_e32 v103, v0
	v_mov_b32_e32 v112, v0
	v_mov_b32_e32 v113, v0
	v_mov_b32_e32 v114, v0
	v_mov_b32_e32 v115, v0
	v_mov_b32_e32 v116, v0
	v_mov_b32_e32 v117, v0
	v_mov_b32_e32 v118, v0
	v_mov_b32_e32 v119, v0
	v_mov_b32_e32 v72, v0
	v_mov_b32_e32 v73, v0
	v_mov_b32_e32 v74, v0
	v_mov_b32_e32 v75, v0
	v_mov_b32_e32 v76, v0
	v_mov_b32_e32 v77, v0
	v_mov_b32_e32 v78, v0
	v_mov_b32_e32 v79, v0
	v_mov_b32_e32 v88, v0
	v_mov_b32_e32 v89, v0
	v_mov_b32_e32 v90, v0
	v_mov_b32_e32 v91, v0
	v_mov_b32_e32 v92, v0
	v_mov_b32_e32 v93, v0
	v_mov_b32_e32 v94, v0
	v_mov_b32_e32 v95, v0
	v_mov_b32_e32 v104, v0
	v_mov_b32_e32 v105, v0
	v_mov_b32_e32 v106, v0
	v_mov_b32_e32 v107, v0
	v_mov_b32_e32 v108, v0
	v_mov_b32_e32 v109, v0
	v_mov_b32_e32 v110, v0
	v_mov_b32_e32 v111, v0
	v_mov_b32_e32 v120, v0
	v_mov_b32_e32 v121, v0
	v_mov_b32_e32 v122, v0
	v_mov_b32_e32 v123, v0
	v_mov_b32_e32 v124, v0
	v_mov_b32_e32 v125, v0
	v_mov_b32_e32 v126, v0
	v_mov_b32_e32 v127, v0
	.p2align 6

; template <class Epi, class Sched, bool ALIGN_EPI = false, bool SP2 = false>
; __device__ __forceinline__ void gemm_phase(PG8_LAS unsigned char* lds, const Gemm g, const Sched& S, const Epi& E) {
;     ...
;         const bool has_next = S.next(ui + 1, nxt);
;         const char* nA = has_next ? (const char*)g.A + (size_t)nxt.pm * tstep : cA; const char* nB = has_next ? (const char*)g.Bt + (size_t)nxt.pn * tstep : cB;
;         for (int t = 0; t < nt; t += 2) {
;             const bool last = (t == nt - 2);
;             const char* a1 = cA + (size_t)(t + 1) * kstep;
;             const char* a2 = last ? nA : cA + (size_t)(t + 2) * kstep; const char* b2 = last ? nB : cB + (size_t)(t + 2) * kstep;
;     ...
; #pragma unroll
;         for (int a = 0; a < 2; ++a)
; #pragma unroll
;             for (int b = 0; b < 2; ++b)
; #pragma unroll
;                 for (int m = 0; m < 4; ++m)
; #pragma unroll
;                     for (int n = 0; n < 2; ++n) acc[a][b][m][n] = (f32x4){0.f, 0.f, 0.f, 0.f};
;         cur = nxt; cA = nA; cB = nB; ++ui;
.LBB0_1072:
	s_ashr_i32 s21, s20, 31
	s_lshl_b64 s[22:23], s[20:21], 19
	s_add_u32 s22, s36, s22
	s_addc_u32 s23, s37, s23
	s_and_b64 s[24:25], s[6:7], exec
	s_cselect_b32 s21, s23, s29
	s_cselect_b32 s33, s22, s28
	s_ashr_i32 s19, s18, 31
	s_lshl_b64 s[24:25], s[18:19], 19
	s_add_u32 s24, s38, s24
	s_addc_u32 s25, s39, s25
	s_and_b64 s[34:35], s[6:7], exec
	s_cselect_b32 s19, s25, s31
	s_cselect_b32 s51, s24, s30
	s_add_u32 s28, s28, 0x40080
	s_addc_u32 s29, s29, 0
	s_add_u32 s52, s30, 0x100
	v_mov_b32_e32 v0, 0
	s_addc_u32 s53, s31, 0
	s_mov_b32 s54, -2
	v_mov_b32_e32 v1, v0
	v_mov_b32_e32 v2, v0
	v_mov_b32_e32 v3, v0
	v_mov_b32_e32 v4, v0
	v_mov_b32_e32 v5, v0
	v_mov_b32_e32 v6, v0
	v_mov_b32_e32 v7, v0
	v_mov_b32_e32 v16, v0
	v_mov_b32_e32 v17, v0
	v_mov_b32_e32 v18, v0
	v_mov_b32_e32 v19, v0
	v_mov_b32_e32 v20, v0
	v_mov_b32_e32 v21, v0
	v_mov_b32_e32 v22, v0
	v_mov_b32_e32 v23, v0
	v_mov_b32_e32 v32, v0
	v_mov_b32_e32 v33, v0
	v_mov_b32_e32 v34, v0
	v_mov_b32_e32 v35, v0
	v_mov_b32_e32 v36, v0
	v_mov_b32_e32 v37, v0
	v_mov_b32_e32 v38, v0
	v_mov_b32_e32 v39, v0
	v_mov_b32_e32 v48, v0
	v_mov_b32_e32 v49, v0
	v_mov_b32_e32 v50, v0
	v_mov_b32_e32 v51, v0
	v_mov_b32_e32 v52, v0
	v_mov_b32_e32 v53, v0
	v_mov_b32_e32 v54, v0
	v_mov_b32_e32 v55, v0
	v_mov_b32_e32 v8, v0
	v_mov_b32_e32 v9, v0
	v_mov_b32_e32 v10, v0
	v_mov_b32_e32 v11, v0
	v_mov_b32_e32 v12, v0
	v_mov_b32_e32 v13, v0
	v_mov_b32_e32 v14, v0
	v_mov_b32_e32 v15, v0
	v_mov_b32_e32 v24, v0
	v_mov_b32_e32 v25, v0
	v_mov_b32_e32 v26, v0
	v_mov_b32_e32 v27, v0
	v_mov_b32_e32 v28, v0
	v_mov_b32_e32 v29, v0
	v_mov_b32_e32 v30, v0
	v_mov_b32_e32 v31, v0
	v_mov_b32_e32 v40, v0
	v_mov_b32_e32 v41, v0
	v_mov_b32_e32 v42, v0
	v_mov_b32_e32 v43, v0
	v_mov_b32_e32 v44, v0
	v_mov_b32_e32 v45, v0
	v_mov_b32_e32 v46, v0
	v_mov_b32_e32 v47, v0
	v_mov_b32_e32 v56, v0
	v_mov_b32_e32 v57, v0
	v_mov_b32_e32 v58, v0
	v_mov_b32_e32 v59, v0
	v_mov_b32_e32 v60, v0
	v_mov_b32_e32 v61, v0
	v_mov_b32_e32 v62, v0
	v_mov_b32_e32 v63, v0
	v_mov_b32_e32 v64, v0
	v_mov_b32_e32 v65, v0
	v_mov_b32_e32 v66, v0
	v_mov_b32_e32 v67, v0
	v_mov_b32_e32 v68, v0
	v_mov_b32_e32 v69, v0
	v_mov_b32_e32 v70, v0
	v_mov_b32_e32 v71, v0
	v_mov_b32_e32 v80, v0
	v_mov_b32_e32 v81, v0
	v_mov_b32_e32 v82, v0
	v_mov_b32_e32 v83, v0
	v_mov_b32_e32 v84, v0
	v_mov_b32_e32 v85, v0
	v_mov_b32_e32 v86, v0
	v_mov_b32_e32 v87, v0
	v_mov_b32_e32 v96, v0
	v_mov_b32_e32 v97, v0
	v_mov_b32_e32 v98, v0
	v_mov_b32_e32 v99, v0
	v_mov_b32_e32 v100, v0
	v_mov_b32_e32 v101, v0
	v_mov_b32_e32 v102, v0
	v_mov_b32_e32 v103, v0
	v_mov_b32_e32 v112, v0
	v_mov_b32_e32 v113, v0
	v_mov_b32_e32 v114, v0
	v_mov_b32_e32 v115, v0
	v_mov_b32_e32 v116, v0
	v_mov_b32_e32 v117, v0
	v_mov_b32_e32 v118, v0
	v_mov_b32_e32 v119, v0
	v_mov_b32_e32 v72, v0
	v_mov_b32_e32 v73, v0
	v_mov_b32_e32 v74, v0
	v_mov_b32_e32 v75, v0
	v_mov_b32_e32 v76, v0
	v_mov_b32_e32 v77, v0
	v_mov_b32_e32 v78, v0
	v_mov_b32_e32 v79, v0
	v_mov_b32_e32 v88, v0
	v_mov_b32_e32 v89, v0
	v_mov_b32_e32 v90, v0
	v_mov_b32_e32 v91, v0
	v_mov_b32_e32 v92, v0
	v_mov_b32_e32 v93, v0
	v_mov_b32_e32 v94, v0
	v_mov_b32_e32 v95, v0
	v_mov_b32_e32 v104, v0
	v_mov_b32_e32 v105, v0
	v_mov_b32_e32 v106, v0
	v_mov_b32_e32 v107, v0
	v_mov_b32_e32 v108, v0
	v_mov_b32_e32 v109, v0
	v_mov_b32_e32 v110, v0
	v_mov_b32_e32 v111, v0
	v_mov_b32_e32 v120, v0
	v_mov_b32_e32 v121, v0
	v_mov_b32_e32 v122, v0
	v_mov_b32_e32 v123, v0
	v_mov_b32_e32 v124, v0
	v_mov_b32_e32 v125, v0
	v_mov_b32_e32 v126, v0
	v_mov_b32_e32 v127, v0
	.p2align 6

; template <class Epi, class Sched, bool ALIGN_EPI = false, bool SP2 = false>
; __device__ __forceinline__ void gemm_phase(PG8_LAS unsigned char* lds, const Gemm g, const Sched& S, const Epi& E) {
;     ...
;         const bool has_next = S.next(ui + 1, nxt);
;         const char* nA = has_next ? (const char*)g.A + (size_t)nxt.pm * tstep : cA; const char* nB = has_next ? (const char*)g.Bt + (size_t)nxt.pn * tstep : cB;
;         for (int t = 0; t < nt; t += 2) {
;             const bool last = (t == nt - 2);
;             const char* a1 = cA + (size_t)(t + 1) * kstep;
;             const char* a2 = last ? nA : cA + (size_t)(t + 2) * kstep; const char* b2 = last ? nB : cB + (size_t)(t + 2) * kstep;
;     ...
; #pragma unroll
;         for (int a = 0; a < 2; ++a)
; #pragma unroll
;             for (int b = 0; b < 2; ++b)
; #pragma unroll
;                 for (int m = 0; m < 4; ++m)
; #pragma unroll
;                     for (int n = 0; n < 2; ++n) acc[a][b][m][n] = (f32x4){0.f, 0.f, 0.f, 0.f};
;         cur = nxt; cA = nA; cB = nB; ++ui;
.LBB0_1150:
	s_ashr_i32 s23, s22, 31
	s_lshl_b64 s[24:25], s[22:23], 20
	s_add_u32 s24, s2, s24
	s_addc_u32 s25, s33, s25
	s_and_b64 s[26:27], s[8:9], exec
	s_cselect_b32 s23, s25, s35
	s_cselect_b32 s29, s24, s34
	s_ashr_i32 s21, s20, 31
	s_lshl_b64 s[26:27], s[20:21], 20
	s_add_u32 s26, s40, s26
	s_addc_u32 s27, s41, s27
	s_and_b64 s[38:39], s[8:9], exec
	s_cselect_b32 s21, s27, s37
	s_cselect_b32 s31, s26, s36
	s_add_u32 s34, s34, 0x80080
	s_addc_u32 s35, s35, 0
	s_add_u32 s54, s36, 0x100
	v_mov_b32_e32 v0, 0
	s_addc_u32 s55, s37, 0
	s_mov_b32 s56, -2
	v_mov_b32_e32 v1, v0
	v_mov_b32_e32 v2, v0
	v_mov_b32_e32 v3, v0
	v_mov_b32_e32 v4, v0
	s_waitcnt lgkmcnt(0)
	v_mov_b32_e32 v5, v0
	v_mov_b32_e32 v6, v0
	v_mov_b32_e32 v7, v0
	v_mov_b32_e32 v16, v0
	v_mov_b32_e32 v17, v0
	v_mov_b32_e32 v18, v0
	v_mov_b32_e32 v19, v0
	v_mov_b32_e32 v20, v0
	v_mov_b32_e32 v21, v0
	v_mov_b32_e32 v22, v0
	v_mov_b32_e32 v23, v0
	v_mov_b32_e32 v32, v0
	v_mov_b32_e32 v33, v0
	v_mov_b32_e32 v34, v0
	v_mov_b32_e32 v35, v0
	v_mov_b32_e32 v36, v0
	v_mov_b32_e32 v37, v0
	v_mov_b32_e32 v38, v0
	v_mov_b32_e32 v39, v0
	v_mov_b32_e32 v48, v0
	v_mov_b32_e32 v49, v0
	v_mov_b32_e32 v50, v0
	v_mov_b32_e32 v51, v0
	v_mov_b32_e32 v52, v0
	v_mov_b32_e32 v53, v0
	v_mov_b32_e32 v54, v0
	v_mov_b32_e32 v55, v0
	v_mov_b32_e32 v8, v0
	v_mov_b32_e32 v9, v0
	v_mov_b32_e32 v10, v0
	v_mov_b32_e32 v11, v0
	v_mov_b32_e32 v12, v0
	v_mov_b32_e32 v13, v0
	v_mov_b32_e32 v14, v0
	v_mov_b32_e32 v15, v0
	v_mov_b32_e32 v24, v0
	v_mov_b32_e32 v25, v0
	v_mov_b32_e32 v26, v0
	v_mov_b32_e32 v27, v0
	v_mov_b32_e32 v28, v0
	v_mov_b32_e32 v29, v0
	v_mov_b32_e32 v30, v0
	v_mov_b32_e32 v31, v0
	v_mov_b32_e32 v40, v0
	v_mov_b32_e32 v41, v0
	v_mov_b32_e32 v42, v0
	v_mov_b32_e32 v43, v0
	v_mov_b32_e32 v44, v0
	v_mov_b32_e32 v45, v0
	v_mov_b32_e32 v46, v0
	v_mov_b32_e32 v47, v0
	v_mov_b32_e32 v56, v0
	v_mov_b32_e32 v57, v0
	v_mov_b32_e32 v58, v0
	v_mov_b32_e32 v59, v0
	v_mov_b32_e32 v60, v0
	v_mov_b32_e32 v61, v0
	v_mov_b32_e32 v62, v0
	v_mov_b32_e32 v63, v0
	v_mov_b32_e32 v64, v0
	v_mov_b32_e32 v65, v0
	v_mov_b32_e32 v66, v0
	v_mov_b32_e32 v67, v0
	v_mov_b32_e32 v68, v0
	v_mov_b32_e32 v69, v0
	v_mov_b32_e32 v70, v0
	v_mov_b32_e32 v71, v0
	v_mov_b32_e32 v80, v0
	v_mov_b32_e32 v81, v0
	v_mov_b32_e32 v82, v0
	v_mov_b32_e32 v83, v0
	v_mov_b32_e32 v84, v0
	v_mov_b32_e32 v85, v0
	v_mov_b32_e32 v86, v0
	v_mov_b32_e32 v87, v0
	v_mov_b32_e32 v96, v0
	v_mov_b32_e32 v97, v0
	v_mov_b32_e32 v98, v0
	v_mov_b32_e32 v99, v0
	v_mov_b32_e32 v100, v0
	v_mov_b32_e32 v101, v0
	v_mov_b32_e32 v102, v0
	v_mov_b32_e32 v103, v0
	v_mov_b32_e32 v112, v0
	v_mov_b32_e32 v113, v0
	v_mov_b32_e32 v114, v0
	v_mov_b32_e32 v115, v0
	v_mov_b32_e32 v116, v0
	v_mov_b32_e32 v117, v0
	v_mov_b32_e32 v118, v0
	v_mov_b32_e32 v119, v0
	v_mov_b32_e32 v72, v0
	v_mov_b32_e32 v73, v0
	v_mov_b32_e32 v74, v0
	v_mov_b32_e32 v75, v0
	v_mov_b32_e32 v76, v0
	v_mov_b32_e32 v77, v0
	v_mov_b32_e32 v78, v0
	v_mov_b32_e32 v79, v0
	v_mov_b32_e32 v88, v0
	v_mov_b32_e32 v89, v0
	v_mov_b32_e32 v90, v0
	v_mov_b32_e32 v91, v0
	v_mov_b32_e32 v92, v0
	v_mov_b32_e32 v93, v0
	v_mov_b32_e32 v94, v0
	v_mov_b32_e32 v95, v0
	v_mov_b32_e32 v104, v0
	v_mov_b32_e32 v105, v0
	v_mov_b32_e32 v106, v0
	v_mov_b32_e32 v107, v0
	v_mov_b32_e32 v108, v0
	v_mov_b32_e32 v109, v0
	v_mov_b32_e32 v110, v0
	v_mov_b32_e32 v111, v0
	v_mov_b32_e32 v120, v0
	v_mov_b32_e32 v121, v0
	v_mov_b32_e32 v122, v0
	v_mov_b32_e32 v123, v0
	v_mov_b32_e32 v124, v0
	v_mov_b32_e32 v125, v0
	v_mov_b32_e32 v126, v0
	v_mov_b32_e32 v127, v0
	.p2align 6

; template <class Epi, class Sched, bool ALIGN_EPI = false, bool SP2 = false>
; __device__ __forceinline__ void gemm_phase(PG8_LAS unsigned char* lds, const Gemm g, const Sched& S, const Epi& E) {
;     ...
;         const bool has_next = S.next(ui + 1, nxt);
;         const char* nA = has_next ? (const char*)g.A + (size_t)nxt.pm * tstep : cA; const char* nB = has_next ? (const char*)g.Bt + (size_t)nxt.pn * tstep : cB;
;         for (int t = 0; t < nt; t += 2) {
;             const bool last = (t == nt - 2);
;             const char* a1 = cA + (size_t)(t + 1) * kstep;
;             const char* a2 = last ? nA : cA + (size_t)(t + 2) * kstep; const char* b2 = last ? nB : cB + (size_t)(t + 2) * kstep;
;     ...
; #pragma unroll
;         for (int a = 0; a < 2; ++a)
; #pragma unroll
;             for (int b = 0; b < 2; ++b)
; #pragma unroll
;                 for (int m = 0; m < 4; ++m)
; #pragma unroll
;                     for (int n = 0; n < 2; ++n) acc[a][b][m][n] = (f32x4){0.f, 0.f, 0.f, 0.f};
;         cur = nxt; cA = nA; cB = nB; ++ui;
.LBB0_1293:
	s_ashr_i32 s21, s20, 31
	s_lshl_b64 s[22:23], s[20:21], 20
	s_add_u32 s22, s33, s22
	s_addc_u32 s23, s36, s23
	s_and_b64 s[24:25], s[8:9], exec
	s_cselect_b32 s21, s23, s29
	s_cselect_b32 s49, s22, s28
	s_ashr_i32 s19, s18, 31
	s_lshl_b64 s[24:25], s[18:19], 20
	s_add_u32 s24, s37, s24
	s_addc_u32 s25, s38, s25
	s_and_b64 s[34:35], s[8:9], exec
	s_cselect_b32 s19, s25, s31
	s_cselect_b32 s50, s24, s30
	s_add_u32 s28, s28, 0x80080
	s_addc_u32 s29, s29, 0
	s_add_u32 s51, s30, 0x100
	v_mov_b32_e32 v0, 0
	s_addc_u32 s52, s31, 0
	s_mov_b32 s53, -2
	v_mov_b32_e32 v1, v0
	v_mov_b32_e32 v2, v0
	v_mov_b32_e32 v3, v0
	v_mov_b32_e32 v4, v0
	v_mov_b32_e32 v5, v0
	v_mov_b32_e32 v6, v0
	v_mov_b32_e32 v7, v0
	v_mov_b32_e32 v12, v0
	v_mov_b32_e32 v13, v0
	v_mov_b32_e32 v14, v0
	v_mov_b32_e32 v15, v0
	v_mov_b32_e32 v20, v0
	v_mov_b32_e32 v21, v0
	v_mov_b32_e32 v22, v0
	v_mov_b32_e32 v23, v0
	v_mov_b32_e32 v28, v0
	v_mov_b32_e32 v29, v0
	v_mov_b32_e32 v30, v0
	v_mov_b32_e32 v31, v0
	v_mov_b32_e32 v36, v0
	v_mov_b32_e32 v37, v0
	v_mov_b32_e32 v38, v0
	v_mov_b32_e32 v39, v0
	v_mov_b32_e32 v44, v0
	v_mov_b32_e32 v45, v0
	v_mov_b32_e32 v46, v0
	v_mov_b32_e32 v47, v0
	v_mov_b32_e32 v52, v0
	v_mov_b32_e32 v53, v0
	v_mov_b32_e32 v54, v0
	v_mov_b32_e32 v55, v0
	v_mov_b32_e32 v8, v0
	v_mov_b32_e32 v9, v0
	v_mov_b32_e32 v10, v0
	v_mov_b32_e32 v11, v0
	v_mov_b32_e32 v16, v0
	v_mov_b32_e32 v17, v0
	v_mov_b32_e32 v18, v0
	v_mov_b32_e32 v19, v0
	v_mov_b32_e32 v24, v0
	v_mov_b32_e32 v25, v0
	v_mov_b32_e32 v26, v0
	v_mov_b32_e32 v27, v0
	v_mov_b32_e32 v32, v0
	v_mov_b32_e32 v33, v0
	v_mov_b32_e32 v34, v0
	v_mov_b32_e32 v35, v0
	v_mov_b32_e32 v40, v0
	v_mov_b32_e32 v41, v0
	v_mov_b32_e32 v42, v0
	v_mov_b32_e32 v43, v0
	v_mov_b32_e32 v48, v0
	v_mov_b32_e32 v49, v0
	v_mov_b32_e32 v50, v0
	v_mov_b32_e32 v51, v0
	v_mov_b32_e32 v56, v0
	v_mov_b32_e32 v57, v0
	v_mov_b32_e32 v58, v0
	v_mov_b32_e32 v59, v0
	v_mov_b32_e32 v60, v0
	v_mov_b32_e32 v61, v0
	v_mov_b32_e32 v62, v0
	v_mov_b32_e32 v63, v0
	v_mov_b32_e32 v64, v0
	v_mov_b32_e32 v65, v0
	v_mov_b32_e32 v66, v0
	v_mov_b32_e32 v67, v0
	v_mov_b32_e32 v68, v0
	v_mov_b32_e32 v69, v0
	v_mov_b32_e32 v70, v0
	v_mov_b32_e32 v71, v0
	v_mov_b32_e32 v76, v0
	v_mov_b32_e32 v77, v0
	v_mov_b32_e32 v78, v0
	v_mov_b32_e32 v79, v0
	v_mov_b32_e32 v84, v0
	v_mov_b32_e32 v85, v0
	v_mov_b32_e32 v86, v0
	v_mov_b32_e32 v87, v0
	v_mov_b32_e32 v92, v0
	v_mov_b32_e32 v93, v0
	v_mov_b32_e32 v94, v0
	v_mov_b32_e32 v95, v0
	v_mov_b32_e32 v100, v0
	v_mov_b32_e32 v101, v0
	v_mov_b32_e32 v102, v0
	v_mov_b32_e32 v103, v0
	v_mov_b32_e32 v108, v0
	v_mov_b32_e32 v109, v0
	v_mov_b32_e32 v110, v0
	v_mov_b32_e32 v111, v0
	v_mov_b32_e32 v116, v0
	v_mov_b32_e32 v117, v0
	v_mov_b32_e32 v118, v0
	v_mov_b32_e32 v119, v0
	v_mov_b32_e32 v72, v0
	v_mov_b32_e32 v73, v0
	v_mov_b32_e32 v74, v0
	v_mov_b32_e32 v75, v0
	v_mov_b32_e32 v80, v0
	v_mov_b32_e32 v81, v0
	v_mov_b32_e32 v82, v0
	v_mov_b32_e32 v83, v0
	v_mov_b32_e32 v88, v0
	v_mov_b32_e32 v89, v0
	v_mov_b32_e32 v90, v0
	v_mov_b32_e32 v91, v0
	v_mov_b32_e32 v96, v0
	v_mov_b32_e32 v97, v0
	v_mov_b32_e32 v98, v0
	v_mov_b32_e32 v99, v0
	v_mov_b32_e32 v104, v0
	v_mov_b32_e32 v105, v0
	v_mov_b32_e32 v106, v0
	v_mov_b32_e32 v107, v0
	v_mov_b32_e32 v112, v0
	v_mov_b32_e32 v113, v0
	v_mov_b32_e32 v114, v0
	v_mov_b32_e32 v115, v0
	v_mov_b32_e32 v120, v0
	v_mov_b32_e32 v121, v0
	v_mov_b32_e32 v122, v0
	v_mov_b32_e32 v123, v0
	v_mov_b32_e32 v124, v0
	v_mov_b32_e32 v125, v0
	v_mov_b32_e32 v126, v0
	v_mov_b32_e32 v127, v0
	.p2align 6

; template <class Epi, class Sched, bool ALIGN_EPI = false, bool SP2 = false>
; __device__ __forceinline__ void gemm_phase(PG8_LAS unsigned char* lds, const Gemm g, const Sched& S, const Epi& E) {
;     ...
;         const bool has_next = S.next(ui + 1, nxt);
;         const char* nA = has_next ? (const char*)g.A + (size_t)nxt.pm * tstep : cA; const char* nB = has_next ? (const char*)g.Bt + (size_t)nxt.pn * tstep : cB;
;         for (int t = 0; t < nt; t += 2) {
;             const bool last = (t == nt - 2);
;             const char* a1 = cA + (size_t)(t + 1) * kstep;
;             const char* a2 = last ? nA : cA + (size_t)(t + 2) * kstep; const char* b2 = last ? nB : cB + (size_t)(t + 2) * kstep;
;     ...
; #pragma unroll
;         for (int a = 0; a < 2; ++a)
; #pragma unroll
;             for (int b = 0; b < 2; ++b)
; #pragma unroll
;                 for (int m = 0; m < 4; ++m)
; #pragma unroll
;                     for (int n = 0; n < 2; ++n) acc[a][b][m][n] = (f32x4){0.f, 0.f, 0.f, 0.f};
;         cur = nxt; cA = nA; cB = nB; ++ui;
.LBB0_1319:
	s_ashr_i32 s25, s24, 31
	s_lshl_b64 s[26:27], s[24:25], 17
	s_add_u32 s26, s33, s26
	s_addc_u32 s27, s55, s27
	s_and_b64 s[28:29], s[10:11], exec
	s_cselect_b32 s25, s27, s39
	s_cselect_b32 s31, s26, s38
	s_ashr_i32 s23, s22, 31
	s_lshl_b64 s[28:29], s[22:23], 17
	s_add_u32 s28, s56, s28
	s_addc_u32 s29, s57, s29
	s_and_b64 s[40:41], s[10:11], exec
	v_mov_b32_e32 v0, 0
	s_cselect_b32 s23, s29, s37
	s_cselect_b32 s35, s28, s36
	s_mov_b32 s44, 0
	s_mov_b64 s[40:41], -1
	s_mov_b64 s[42:43], 0
	v_mov_b32_e32 v1, v0
	v_mov_b32_e32 v2, v0
	v_mov_b32_e32 v3, v0
	v_mov_b32_e32 v4, v0
	s_waitcnt lgkmcnt(0)
	v_mov_b32_e32 v5, v0
	v_mov_b32_e32 v6, v0
	v_mov_b32_e32 v7, v0
	v_mov_b32_e32 v16, v0
	v_mov_b32_e32 v17, v0
	v_mov_b32_e32 v18, v0
	v_mov_b32_e32 v19, v0
	v_mov_b32_e32 v20, v0
	v_mov_b32_e32 v21, v0
	v_mov_b32_e32 v22, v0
	v_mov_b32_e32 v23, v0
	v_mov_b32_e32 v32, v0
	v_mov_b32_e32 v33, v0
	v_mov_b32_e32 v34, v0
	v_mov_b32_e32 v35, v0
	v_mov_b32_e32 v36, v0
	v_mov_b32_e32 v37, v0
	v_mov_b32_e32 v38, v0
	v_mov_b32_e32 v39, v0
	v_mov_b32_e32 v48, v0
	v_mov_b32_e32 v49, v0
	v_mov_b32_e32 v50, v0
	v_mov_b32_e32 v51, v0
	v_mov_b32_e32 v52, v0
	v_mov_b32_e32 v53, v0
	v_mov_b32_e32 v54, v0
	v_mov_b32_e32 v55, v0
	v_mov_b32_e32 v8, v0
	v_mov_b32_e32 v9, v0
	v_mov_b32_e32 v10, v0
	v_mov_b32_e32 v11, v0
	v_mov_b32_e32 v12, v0
	v_mov_b32_e32 v13, v0
	v_mov_b32_e32 v14, v0
	v_mov_b32_e32 v15, v0
	v_mov_b32_e32 v24, v0
	v_mov_b32_e32 v25, v0
	v_mov_b32_e32 v26, v0
	v_mov_b32_e32 v27, v0
	v_mov_b32_e32 v28, v0
	v_mov_b32_e32 v29, v0
	v_mov_b32_e32 v30, v0
	v_mov_b32_e32 v31, v0
	v_mov_b32_e32 v40, v0
	v_mov_b32_e32 v41, v0
	v_mov_b32_e32 v42, v0
	v_mov_b32_e32 v43, v0
	v_mov_b32_e32 v44, v0
	v_mov_b32_e32 v45, v0
	v_mov_b32_e32 v46, v0
	v_mov_b32_e32 v47, v0
	v_mov_b32_e32 v56, v0
	v_mov_b32_e32 v57, v0
	v_mov_b32_e32 v58, v0
	v_mov_b32_e32 v59, v0
	v_mov_b32_e32 v60, v0
	v_mov_b32_e32 v61, v0
	v_mov_b32_e32 v62, v0
	v_mov_b32_e32 v63, v0
	v_mov_b32_e32 v64, v0
	v_mov_b32_e32 v65, v0
	v_mov_b32_e32 v66, v0
	v_mov_b32_e32 v67, v0
	v_mov_b32_e32 v68, v0
	v_mov_b32_e32 v69, v0
	v_mov_b32_e32 v70, v0
	v_mov_b32_e32 v71, v0
	v_mov_b32_e32 v80, v0
	v_mov_b32_e32 v81, v0
	v_mov_b32_e32 v82, v0
	v_mov_b32_e32 v83, v0
	v_mov_b32_e32 v84, v0
	v_mov_b32_e32 v85, v0
	v_mov_b32_e32 v86, v0
	v_mov_b32_e32 v87, v0
	v_mov_b32_e32 v96, v0
	v_mov_b32_e32 v97, v0
	v_mov_b32_e32 v98, v0
	v_mov_b32_e32 v99, v0
	v_mov_b32_e32 v100, v0
	v_mov_b32_e32 v101, v0
	v_mov_b32_e32 v102, v0
	v_mov_b32_e32 v103, v0
	v_mov_b32_e32 v112, v0
	v_mov_b32_e32 v113, v0
	v_mov_b32_e32 v114, v0
	v_mov_b32_e32 v115, v0
	v_mov_b32_e32 v116, v0
	v_mov_b32_e32 v117, v0
	v_mov_b32_e32 v118, v0
	v_mov_b32_e32 v119, v0
	v_mov_b32_e32 v72, v0
	v_mov_b32_e32 v73, v0
	v_mov_b32_e32 v74, v0
	v_mov_b32_e32 v75, v0
	v_mov_b32_e32 v76, v0
	v_mov_b32_e32 v77, v0
	v_mov_b32_e32 v78, v0
	v_mov_b32_e32 v79, v0
	v_mov_b32_e32 v88, v0
	v_mov_b32_e32 v89, v0
	v_mov_b32_e32 v90, v0
	v_mov_b32_e32 v91, v0
	v_mov_b32_e32 v92, v0
	v_mov_b32_e32 v93, v0
	v_mov_b32_e32 v94, v0
	v_mov_b32_e32 v95, v0
	v_mov_b32_e32 v104, v0
	v_mov_b32_e32 v105, v0
	v_mov_b32_e32 v106, v0
	v_mov_b32_e32 v107, v0
	v_mov_b32_e32 v108, v0
	v_mov_b32_e32 v109, v0
	v_mov_b32_e32 v110, v0
	v_mov_b32_e32 v111, v0
	v_mov_b32_e32 v120, v0
	v_mov_b32_e32 v121, v0
	v_mov_b32_e32 v122, v0
	v_mov_b32_e32 v123, v0
	v_mov_b32_e32 v124, v0
	v_mov_b32_e32 v125, v0
	v_mov_b32_e32 v126, v0
	v_mov_b32_e32 v127, v0
	.p2align 6

; template <class Epi, class Sched, bool ALIGN_EPI = false, bool SP2 = false>
; __device__ __forceinline__ void gemm_phase(PG8_LAS unsigned char* lds, const Gemm g, const Sched& S, const Epi& E) {
;     ...
;         const bool has_next = S.next(ui + 1, nxt);
;         const char* nA = has_next ? (const char*)g.A + (size_t)nxt.pm * tstep : cA; const char* nB = has_next ? (const char*)g.Bt + (size_t)nxt.pn * tstep : cB;
;         for (int t = 0; t < nt; t += 2) {
;             const bool last = (t == nt - 2);
;             const char* a1 = cA + (size_t)(t + 1) * kstep;
;             const char* a2 = last ? nA : cA + (size_t)(t + 2) * kstep; const char* b2 = last ? nB : cB + (size_t)(t + 2) * kstep;
;     ...
; #pragma unroll
;         for (int a = 0; a < 2; ++a)
; #pragma unroll
;             for (int b = 0; b < 2; ++b)
; #pragma unroll
;                 for (int m = 0; m < 4; ++m)
; #pragma unroll
;                     for (int n = 0; n < 2; ++n) acc[a][b][m][n] = (f32x4){0.f, 0.f, 0.f, 0.f};
;         cur = nxt; cA = nA; cB = nB; ++ui;
.LBB0_1413:
	s_ashr_i32 s25, s24, 31
	s_lshl_b64 s[26:27], s[24:25], 22
	s_add_u32 s26, s33, s26
	s_addc_u32 s27, s42, s27
	s_and_b64 s[28:29], s[10:11], exec
	s_cselect_b32 s25, s27, s37
	s_cselect_b32 s31, s26, s36
	s_ashr_i32 s23, s22, 31
	s_lshl_b64 s[28:29], s[22:23], 22
	s_add_u32 s28, s43, s28
	s_addc_u32 s29, s44, s29
	s_and_b64 s[40:41], s[10:11], exec
	s_cselect_b32 s23, s29, s39
	s_cselect_b32 s35, s28, s38
	s_add_u32 s36, s36, 0x200080
	s_addc_u32 s37, s37, 0
	s_add_u32 s56, s38, 0x100
	v_mov_b32_e32 v0, 0
	s_addc_u32 s57, s39, 0
	s_mov_b32 s58, -2
	v_mov_b32_e32 v1, v0
	v_mov_b32_e32 v2, v0
	v_mov_b32_e32 v3, v0
	v_mov_b32_e32 v4, v0
	s_waitcnt lgkmcnt(0)
	v_mov_b32_e32 v5, v0
	v_mov_b32_e32 v6, v0
	v_mov_b32_e32 v7, v0
	v_mov_b32_e32 v16, v0
	v_mov_b32_e32 v17, v0
	v_mov_b32_e32 v18, v0
	v_mov_b32_e32 v19, v0
	v_mov_b32_e32 v20, v0
	v_mov_b32_e32 v21, v0
	v_mov_b32_e32 v22, v0
	v_mov_b32_e32 v23, v0
	v_mov_b32_e32 v32, v0
	v_mov_b32_e32 v33, v0
	v_mov_b32_e32 v34, v0
	v_mov_b32_e32 v35, v0
	v_mov_b32_e32 v36, v0
	v_mov_b32_e32 v37, v0
	v_mov_b32_e32 v38, v0
	v_mov_b32_e32 v39, v0
	v_mov_b32_e32 v48, v0
	v_mov_b32_e32 v49, v0
	v_mov_b32_e32 v50, v0
	v_mov_b32_e32 v51, v0
	v_mov_b32_e32 v52, v0
	v_mov_b32_e32 v53, v0
	v_mov_b32_e32 v54, v0
	v_mov_b32_e32 v55, v0
	v_mov_b32_e32 v8, v0
	v_mov_b32_e32 v9, v0
	v_mov_b32_e32 v10, v0
	v_mov_b32_e32 v11, v0
	v_mov_b32_e32 v12, v0
	v_mov_b32_e32 v13, v0
	v_mov_b32_e32 v14, v0
	v_mov_b32_e32 v15, v0
	v_mov_b32_e32 v24, v0
	v_mov_b32_e32 v25, v0
	v_mov_b32_e32 v26, v0
	v_mov_b32_e32 v27, v0
	v_mov_b32_e32 v28, v0
	v_mov_b32_e32 v29, v0
	v_mov_b32_e32 v30, v0
	v_mov_b32_e32 v31, v0
	v_mov_b32_e32 v40, v0
	v_mov_b32_e32 v41, v0
	v_mov_b32_e32 v42, v0
	v_mov_b32_e32 v43, v0
	v_mov_b32_e32 v44, v0
	v_mov_b32_e32 v45, v0
	v_mov_b32_e32 v46, v0
	v_mov_b32_e32 v47, v0
	v_mov_b32_e32 v56, v0
	v_mov_b32_e32 v57, v0
	v_mov_b32_e32 v58, v0
	v_mov_b32_e32 v59, v0
	v_mov_b32_e32 v60, v0
	v_mov_b32_e32 v61, v0
	v_mov_b32_e32 v62, v0
	v_mov_b32_e32 v63, v0
	v_mov_b32_e32 v64, v0
	v_mov_b32_e32 v65, v0
	v_mov_b32_e32 v66, v0
	v_mov_b32_e32 v67, v0
	v_mov_b32_e32 v68, v0
	v_mov_b32_e32 v69, v0
	v_mov_b32_e32 v70, v0
	v_mov_b32_e32 v71, v0
	v_mov_b32_e32 v80, v0
	v_mov_b32_e32 v81, v0
	v_mov_b32_e32 v82, v0
	v_mov_b32_e32 v83, v0
	v_mov_b32_e32 v84, v0
	v_mov_b32_e32 v85, v0
	v_mov_b32_e32 v86, v0
	v_mov_b32_e32 v87, v0
	v_mov_b32_e32 v96, v0
	v_mov_b32_e32 v97, v0
	v_mov_b32_e32 v98, v0
	v_mov_b32_e32 v99, v0
	v_mov_b32_e32 v100, v0
	v_mov_b32_e32 v101, v0
	v_mov_b32_e32 v102, v0
	v_mov_b32_e32 v103, v0
	v_mov_b32_e32 v112, v0
	v_mov_b32_e32 v113, v0
	v_mov_b32_e32 v114, v0
	v_mov_b32_e32 v115, v0
	v_mov_b32_e32 v116, v0
	v_mov_b32_e32 v117, v0
	v_mov_b32_e32 v118, v0
	v_mov_b32_e32 v119, v0
	v_mov_b32_e32 v72, v0
	v_mov_b32_e32 v73, v0
	v_mov_b32_e32 v74, v0
	v_mov_b32_e32 v75, v0
	v_mov_b32_e32 v76, v0
	v_mov_b32_e32 v77, v0
	v_mov_b32_e32 v78, v0
	v_mov_b32_e32 v79, v0
	v_mov_b32_e32 v88, v0
	v_mov_b32_e32 v89, v0
	v_mov_b32_e32 v90, v0
	v_mov_b32_e32 v91, v0
	v_mov_b32_e32 v92, v0
	v_mov_b32_e32 v93, v0
	v_mov_b32_e32 v94, v0
	v_mov_b32_e32 v95, v0
	v_mov_b32_e32 v104, v0
	v_mov_b32_e32 v105, v0
	v_mov_b32_e32 v106, v0
	v_mov_b32_e32 v107, v0
	v_mov_b32_e32 v108, v0
	v_mov_b32_e32 v109, v0
	v_mov_b32_e32 v110, v0
	v_mov_b32_e32 v111, v0
	v_mov_b32_e32 v120, v0
	v_mov_b32_e32 v121, v0
	v_mov_b32_e32 v122, v0
	v_mov_b32_e32 v123, v0
	v_mov_b32_e32 v124, v0
	v_mov_b32_e32 v125, v0
	v_mov_b32_e32 v126, v0
	v_mov_b32_e32 v127, v0
	.p2align 6

; template <class Epi, class Sched, bool ALIGN_EPI = false, bool SP2 = false>
; __device__ __forceinline__ void gemm_phase(PG8_LAS unsigned char* lds, const Gemm g, const Sched& S, const Epi& E) {
;     ...
;         const bool has_next = S.next(ui + 1, nxt);
;         const char* nA = has_next ? (const char*)g.A + (size_t)nxt.pm * tstep : cA; const char* nB = has_next ? (const char*)g.Bt + (size_t)nxt.pn * tstep : cB;
;         for (int t = 0; t < nt; t += 2) {
;             const bool last = (t == nt - 2);
;             const char* a1 = cA + (size_t)(t + 1) * kstep;
;             const char* a2 = last ? nA : cA + (size_t)(t + 2) * kstep; const char* b2 = last ? nB : cB + (size_t)(t + 2) * kstep;
;     ...
; #pragma unroll
;         for (int a = 0; a < 2; ++a)
; #pragma unroll
;             for (int b = 0; b < 2; ++b)
; #pragma unroll
;                 for (int m = 0; m < 4; ++m)
; #pragma unroll
;                     for (int n = 0; n < 2; ++n) acc[a][b][m][n] = (f32x4){0.f, 0.f, 0.f, 0.f};
;         cur = nxt; cA = nA; cB = nB; ++ui;
.LBB0_1561:
	s_ashr_i32 s21, s20, 31
	s_lshl_b64 s[22:23], s[20:21], 20
	s_add_u32 s22, s33, s22
	s_addc_u32 s23, s36, s23
	s_and_b64 s[24:25], s[0:1], exec
	s_cselect_b32 s21, s23, s29
	s_cselect_b32 s49, s22, s28
	s_ashr_i32 s19, s18, 31
	s_lshl_b64 s[24:25], s[18:19], 20
	s_add_u32 s24, s37, s24
	s_addc_u32 s25, s38, s25
	s_and_b64 s[34:35], s[0:1], exec
	s_cselect_b32 s19, s25, s31
	s_cselect_b32 s50, s24, s30
	s_add_u32 s28, s28, 0x80080
	s_addc_u32 s29, s29, 0
	s_add_u32 s51, s30, 0x100
	v_mov_b32_e32 v0, 0
	s_addc_u32 s52, s31, 0
	s_mov_b32 s53, -2
	v_mov_b32_e32 v1, v0
	v_mov_b32_e32 v2, v0
	v_mov_b32_e32 v3, v0
	v_mov_b32_e32 v4, v0
	v_mov_b32_e32 v5, v0
	v_mov_b32_e32 v6, v0
	v_mov_b32_e32 v7, v0
	v_mov_b32_e32 v16, v0
	v_mov_b32_e32 v17, v0
	v_mov_b32_e32 v18, v0
	v_mov_b32_e32 v19, v0
	v_mov_b32_e32 v20, v0
	v_mov_b32_e32 v21, v0
	v_mov_b32_e32 v22, v0
	v_mov_b32_e32 v23, v0
	v_mov_b32_e32 v32, v0
	v_mov_b32_e32 v33, v0
	v_mov_b32_e32 v34, v0
	v_mov_b32_e32 v35, v0
	v_mov_b32_e32 v36, v0
	v_mov_b32_e32 v37, v0
	v_mov_b32_e32 v38, v0
	v_mov_b32_e32 v39, v0
	v_mov_b32_e32 v48, v0
	v_mov_b32_e32 v49, v0
	v_mov_b32_e32 v50, v0
	v_mov_b32_e32 v51, v0
	v_mov_b32_e32 v52, v0
	v_mov_b32_e32 v53, v0
	v_mov_b32_e32 v54, v0
	v_mov_b32_e32 v55, v0
	v_mov_b32_e32 v8, v0
	v_mov_b32_e32 v9, v0
	v_mov_b32_e32 v10, v0
	v_mov_b32_e32 v11, v0
	v_mov_b32_e32 v12, v0
	v_mov_b32_e32 v13, v0
	v_mov_b32_e32 v14, v0
	v_mov_b32_e32 v15, v0
	v_mov_b32_e32 v24, v0
	v_mov_b32_e32 v25, v0
	v_mov_b32_e32 v26, v0
	v_mov_b32_e32 v27, v0
	v_mov_b32_e32 v28, v0
	v_mov_b32_e32 v29, v0
	v_mov_b32_e32 v30, v0
	v_mov_b32_e32 v31, v0
	v_mov_b32_e32 v40, v0
	v_mov_b32_e32 v41, v0
	v_mov_b32_e32 v42, v0
	v_mov_b32_e32 v43, v0
	v_mov_b32_e32 v44, v0
	v_mov_b32_e32 v45, v0
	v_mov_b32_e32 v46, v0
	v_mov_b32_e32 v47, v0
	v_mov_b32_e32 v56, v0
	v_mov_b32_e32 v57, v0
	v_mov_b32_e32 v58, v0
	v_mov_b32_e32 v59, v0
	v_mov_b32_e32 v60, v0
	v_mov_b32_e32 v61, v0
	v_mov_b32_e32 v62, v0
	v_mov_b32_e32 v63, v0
	v_mov_b32_e32 v64, v0
	v_mov_b32_e32 v65, v0
	v_mov_b32_e32 v66, v0
	v_mov_b32_e32 v67, v0
	v_mov_b32_e32 v68, v0
	v_mov_b32_e32 v69, v0
	v_mov_b32_e32 v70, v0
	v_mov_b32_e32 v71, v0
	v_mov_b32_e32 v80, v0
	v_mov_b32_e32 v81, v0
	v_mov_b32_e32 v82, v0
	v_mov_b32_e32 v83, v0
	v_mov_b32_e32 v84, v0
	v_mov_b32_e32 v85, v0
	v_mov_b32_e32 v86, v0
	v_mov_b32_e32 v87, v0
	v_mov_b32_e32 v96, v0
	v_mov_b32_e32 v97, v0
	v_mov_b32_e32 v98, v0
	v_mov_b32_e32 v99, v0
	v_mov_b32_e32 v100, v0
	v_mov_b32_e32 v101, v0
	v_mov_b32_e32 v102, v0
	v_mov_b32_e32 v103, v0
	v_mov_b32_e32 v112, v0
	v_mov_b32_e32 v113, v0
	v_mov_b32_e32 v114, v0
	v_mov_b32_e32 v115, v0
	v_mov_b32_e32 v116, v0
	v_mov_b32_e32 v117, v0
	v_mov_b32_e32 v118, v0
	v_mov_b32_e32 v119, v0
	v_mov_b32_e32 v72, v0
	v_mov_b32_e32 v73, v0
	v_mov_b32_e32 v74, v0
	v_mov_b32_e32 v75, v0
	v_mov_b32_e32 v76, v0
	v_mov_b32_e32 v77, v0
	v_mov_b32_e32 v78, v0
	v_mov_b32_e32 v79, v0
	v_mov_b32_e32 v88, v0
	v_mov_b32_e32 v89, v0
	v_mov_b32_e32 v90, v0
	v_mov_b32_e32 v91, v0
	v_mov_b32_e32 v92, v0
	v_mov_b32_e32 v93, v0
	v_mov_b32_e32 v94, v0
	v_mov_b32_e32 v95, v0
	v_mov_b32_e32 v104, v0
	v_mov_b32_e32 v105, v0
	v_mov_b32_e32 v106, v0
	v_mov_b32_e32 v107, v0
	v_mov_b32_e32 v108, v0
	v_mov_b32_e32 v109, v0
	v_mov_b32_e32 v110, v0
	v_mov_b32_e32 v111, v0
	v_mov_b32_e32 v120, v0
	v_mov_b32_e32 v121, v0
	v_mov_b32_e32 v122, v0
	v_mov_b32_e32 v123, v0
	v_mov_b32_e32 v124, v0
	v_mov_b32_e32 v125, v0
	v_mov_b32_e32 v126, v0
	v_mov_b32_e32 v127, v0
	.p2align 6
